# combine phase: the 12 loop-invariant per-column parameter vector loads (each followed by vmcnt(0)) hoisted out of the row loop into registers; only the end-of-row wait remains
# speedup vs baseline: 1.0213x; 1.0131x over previous
.LBB0_18:
	s_or_b64 exec, exec, s[8:9]
	s_and_saveexec_b64 s[20:21], vcc
	s_cbranch_execz .LBB0_64
	s_waitcnt lgkmcnt(0)
	s_load_dwordx2 s[12:13], s[0:1], 0x28
	s_load_dwordx4 s[8:11], s[0:1], 0x10
	s_lshl_b32 s14, s90, 10
	s_ashr_i32 s15, s14, 31
	s_lshl_b64 s[14:15], s[14:15], 2
	s_waitcnt lgkmcnt(0)
	s_add_u32 s12, s12, s14
	s_addc_u32 s13, s13, s15
	s_add_u32 s8, s8, s14
	s_addc_u32 s9, s9, s15
	s_add_u32 s10, s10, s14
	s_addc_u32 s11, s11, s15
	s_add_i32 s14, s90, 1
	s_mul_hi_i32 s15, s14, 0x55555556
	s_lshr_b32 s22, s15, 31
	s_add_i32 s15, s15, s22
	s_mul_i32 s15, s15, 3
	s_sub_i32 s14, s14, s15
	s_cmp_lt_i32 s48, 28
	v_and_b32_e32 v4, 64, v168
	s_cselect_b32 s24, s14, -1
	v_xor_b32_e32 v0, 16, v168
	v_add_u32_e32 v4, 64, v4
	v_cmp_lt_i32_e32 vcc, v0, v4
	s_cmp_lg_u32 s24, 1
	s_cselect_b64 s[22:23], -1, 0
	v_cndmask_b32_e32 v0, v168, v0, vcc
	s_cmp_gt_i32 s24, -1
	v_lshlrev_b32_e32 v37, 2, v0
	v_xor_b32_e32 v0, 32, v168
	s_cselect_b64 s[24:25], -1, 0
	s_add_i32 s2, s2, s58
	v_cmp_lt_i32_e32 vcc, v0, v4
	s_load_dwordx2 s[14:15], s[0:1], 0xf8
	v_add_u32_e32 v4, s2, v3
	v_cndmask_b32_e32 v0, v168, v0, vcc
	v_ashrrev_i32_e32 v5, 31, v4
	v_lshlrev_b32_e32 v36, 2, v2
	v_lshlrev_b32_e32 v118, 2, v0
	v_lshlrev_b32_e32 v0, 4, v2
	v_lshlrev_b32_e32 v46, 3, v2
	v_lshlrev_b64 v[2:3], 11, v[4:5]
	v_lshlrev_b64 v[6:7], 12, v[4:5]
	v_lshl_add_u64 v[48:49], s[18:19], 0, v[2:3]
	v_lshlrev_b64 v[2:3], 12, v[88:89]
	v_or_b32_e32 v6, v6, v0
	v_lshl_add_u64 v[50:51], s[18:19], 0, v[2:3]
	v_lshlrev_b64 v[4:5], 11, v[88:89]
	v_or_b32_e32 v2, v2, v0
	v_lshl_add_u64 v[44:45], s[6:7], 0, v[6:7]
	v_lshl_add_u64 v[52:53], s[18:19], 0, v[4:5]
	s_waitcnt lgkmcnt(0)
	v_lshl_add_u64 v[54:55], s[14:15], 0, v[2:3]
	s_waitcnt vmcnt(15)
	v_mov_b64_e32 v[2:3], v[30:31]
	s_waitcnt vmcnt(14)
	v_mov_b64_e32 v[6:7], v[26:27]
	s_waitcnt vmcnt(5)
	v_mov_b64_e32 v[10:11], v[22:23]
	s_waitcnt vmcnt(4)
	v_mov_b64_e32 v[14:15], v[18:19]
	v_lshl_add_u64 v[38:39], s[8:9], 0, v[0:1]
	v_lshl_add_u64 v[40:41], s[10:11], 0, v[0:1]
	v_lshl_add_u64 v[42:43], s[12:13], 0, v[0:1]
	global_load_dwordx4 v[176:179], v[38:39], off
	global_load_dwordx4 v[180:183], v[38:39], off offset:1024
	global_load_dwordx4 v[184:187], v[38:39], off offset:2048
	global_load_dwordx4 v[188:191], v[38:39], off offset:3072
	global_load_dwordx4 v[192:195], v[40:41], off
	global_load_dwordx4 v[196:199], v[40:41], off offset:1024
	global_load_dwordx4 v[206:209], v[40:41], off offset:2048
	global_load_dwordx4 v[210:213], v[40:41], off offset:3072
	global_load_dwordx4 v[214:217], v[42:43], off
	global_load_dwordx4 v[218:221], v[42:43], off offset:1024
	global_load_dwordx4 v[222:225], v[42:43], off offset:2048
	global_load_dwordx4 v[226:229], v[42:43], off offset:3072
	v_mov_b32_e32 v47, v1
	s_mov_b64 s[26:27], 0
	s_mov_b64 s[28:29], 0
	s_waitcnt vmcnt(0)
	v_mov_b64_e32 v[64:65], v[34:35]
	v_mov_b64_e32 v[66:67], v[80:81]
	v_mov_b64_e32 v[68:69], v[82:83]
	v_mov_b64_e32 v[70:71], v[106:107]
	v_mov_b64_e32 v[56:57], v[84:85]
	v_mov_b64_e32 v[58:59], v[90:91]
	v_mov_b64_e32 v[60:61], v[94:95]
	v_mov_b64_e32 v[62:63], v[98:99]
	v_mov_b64_e32 v[4:5], v[32:33]
	v_mov_b64_e32 v[8:9], v[28:29]
	v_mov_b64_e32 v[12:13], v[24:25]
	v_mov_b64_e32 v[16:17], v[20:21]
	s_branch .LBB0_26

.LBB0_28:
	s_or_b64 exec, exec, s[8:9]
	v_lshlrev_b32_e32 v102, 16, v98
	v_and_b32_e32 v103, 0xffff0000, v98
	v_lshlrev_b32_e32 v98, 16, v99
	v_and_b32_e32 v99, 0xffff0000, v99
	v_pk_fma_f32 v[116:117], v[30:31], s[86:87], v[102:103] op_sel_hi:[1,0,1]
	v_lshlrev_b32_e32 v30, 16, v94
	v_and_b32_e32 v31, 0xffff0000, v94
	v_pk_fma_f32 v[114:115], v[32:33], s[86:87], v[98:99] op_sel_hi:[1,0,1]
	v_add_f32_e32 v0, v116, v117
	v_lshlrev_b32_e32 v32, 16, v95
	v_and_b32_e32 v33, 0xffff0000, v95
	v_pk_fma_f32 v[104:105], v[26:27], s[86:87], v[30:31] op_sel_hi:[1,0,1]
	v_add_f32_e32 v0, v114, v0
	v_pk_fma_f32 v[102:103], v[28:29], s[86:87], v[32:33] op_sel_hi:[1,0,1]
	v_add_f32_e32 v26, v104, v105
	v_add_f32_e32 v0, v115, v0
	v_add_f32_e32 v26, v102, v26
	v_add_f32_e32 v0, 0, v0
	v_and_b32_e32 v111, 0xffff0000, v96
	v_add_f32_e32 v26, v103, v26
	v_and_b32_e32 v99, 0xffff0000, v100
	v_lshlrev_b32_e32 v110, 16, v96
	v_mul_f32_e32 v89, v111, v111
	v_add_f32_e32 v0, v26, v0
	v_lshlrev_b32_e32 v98, 16, v100
	v_mul_f32_e32 v26, v99, v99
	v_lshlrev_b32_e32 v112, 16, v97
	v_fmac_f32_e32 v89, v110, v110
	v_lshlrev_b32_e32 v100, 16, v101
	v_fmac_f32_e32 v26, v98, v98
	v_and_b32_e32 v113, 0xffff0000, v97
	v_fmac_f32_e32 v89, v112, v112
	v_and_b32_e32 v101, 0xffff0000, v101
	v_fmac_f32_e32 v26, v100, v100
	v_fmac_f32_e32 v89, v113, v113
	v_fmac_f32_e32 v26, v101, v101
	v_add_f32_e32 v30, v89, v26
	v_lshlrev_b32_e32 v26, 16, v90
	v_and_b32_e32 v27, 0xffff0000, v90
	v_lshlrev_b32_e32 v28, 16, v91
	v_and_b32_e32 v29, 0xffff0000, v91
	v_pk_fma_f32 v[96:97], v[22:23], s[86:87], v[26:27] op_sel_hi:[1,0,1]
	v_pk_fma_f32 v[94:95], v[24:25], s[86:87], v[28:29] op_sel_hi:[1,0,1]
	v_add_f32_e32 v22, v96, v97
	v_add_f32_e32 v22, v94, v22
	v_add_f32_e32 v22, v95, v22
	v_and_b32_e32 v91, 0xffff0000, v92
	v_add_f32_e32 v0, v22, v0
	v_lshlrev_b32_e32 v90, 16, v92
	v_mul_f32_e32 v22, v91, v91
	v_lshlrev_b32_e32 v92, 16, v93
	v_fmac_f32_e32 v22, v90, v90
	v_and_b32_e32 v93, 0xffff0000, v93
	v_fmac_f32_e32 v22, v92, v92
	v_fmac_f32_e32 v22, v93, v93
	v_lshlrev_b32_e32 v24, 16, v84
	v_and_b32_e32 v25, 0xffff0000, v84
	v_add_f32_e32 v30, v22, v30
	v_lshlrev_b32_e32 v22, 16, v85
	v_and_b32_e32 v23, 0xffff0000, v85
	v_pk_fma_f32 v[24:25], v[18:19], s[86:87], v[24:25] op_sel_hi:[1,0,1]
	v_pk_fma_f32 v[22:23], v[20:21], s[86:87], v[22:23] op_sel_hi:[1,0,1]
	v_add_f32_e32 v18, v24, v25
	v_add_f32_e32 v18, v22, v18
	v_add_f32_e32 v18, v23, v18
	v_add_f32_e32 v0, v18, v0
	v_and_b32_e32 v27, 0xffff0000, v86
	v_lshlrev_b32_e32 v26, 16, v86
	v_mul_f32_e32 v18, v27, v27
	v_add_f32_dpp v0, v0, v0 quad_perm:[1,0,3,2] row_mask:0xf bank_mask:0xf bound_ctrl:1
	v_lshlrev_b32_e32 v28, 16, v87
	v_fmac_f32_e32 v18, v26, v26
	v_add_f32_dpp v0, v0, v0 quad_perm:[2,3,0,1] row_mask:0xf bank_mask:0xf bound_ctrl:1
	v_and_b32_e32 v29, 0xffff0000, v87
	v_fmac_f32_e32 v18, v28, v28
	v_add_f32_dpp v0, v0, v0 row_ror:4 row_mask:0xf bank_mask:0xf bound_ctrl:1
	v_fmac_f32_e32 v18, v29, v29
	v_add_f32_e32 v89, v18, v30
	v_add_f32_dpp v0, v0, v0 row_ror:8 row_mask:0xf bank_mask:0xf bound_ctrl:1
	ds_bpermute_b32 v18, v37, v0
	v_mov_b32_dpp v19, v89 quad_perm:[1,0,3,2] row_mask:0xf bank_mask:0xf bound_ctrl:1
	s_mov_b32 s2, 0x3a800000
	s_mov_b64 s[14:15], -1
	s_waitcnt lgkmcnt(0)
	v_add_f32_e32 v0, v0, v18
	ds_bpermute_b32 v18, v118, v0
	s_waitcnt lgkmcnt(0)
	v_add_f32_e32 v0, v0, v18
	v_fmamk_f32 v117, v0, 0xba800000, v117
	v_fmac_f32_e32 v116, 0xba800000, v0
	v_fmamk_f32 v85, v0, 0xba800000, v105
	v_fmac_f32_e32 v104, 0xba800000, v0
	v_mov_b32_e32 v84, v117
	v_fmac_f32_e32 v114, 0xba800000, v0
	v_fmac_f32_e32 v102, 0xba800000, v0
	v_mov_b32_e32 v20, v116
	v_mov_b32_e32 v21, v104
	v_pk_mul_f32 v[30:31], v[84:85], v[84:85]
	v_fmamk_f32 v33, v0, 0xba800000, v97
	v_fmac_f32_e32 v96, 0xba800000, v0
	v_fmamk_f32 v32, v0, 0xba800000, v25
	v_fmamk_f32 v115, v0, 0xba800000, v115
	v_pk_fma_f32 v[20:21], v[20:21], v[20:21], v[30:31]
	v_mov_b32_e32 v30, v114
	v_mov_b32_e32 v31, v102
	v_fmac_f32_e32 v94, 0xba800000, v0
	v_fmac_f32_e32 v24, 0xba800000, v0
	v_mov_b32_e32 v25, v96
	v_pk_mul_f32 v[86:87], v[32:33], v[32:33]
	v_fmamk_f32 v109, v0, 0xba800000, v103
	v_pk_fma_f32 v[20:21], v[30:31], v[30:31], v[20:21]
	v_mov_b32_e32 v108, v115
	v_fmamk_f32 v30, v0, 0xba800000, v23
	v_fmac_f32_e32 v22, 0xba800000, v0
	v_pk_fma_f32 v[86:87], v[24:25], v[24:25], v[86:87]
	v_mov_b32_e32 v23, v94
	v_pk_fma_f32 v[20:21], v[108:109], v[108:109], v[20:21]
	v_fmamk_f32 v31, v0, 0xba800000, v95
	v_pk_fma_f32 v[86:87], v[22:23], v[22:23], v[86:87]
	v_pk_add_f32 v[20:21], v[20:21], v[20:21] op_sel:[0,1] op_sel_hi:[1,0]
	v_pk_fma_f32 v[86:87], v[30:31], v[30:31], v[86:87]
	s_nop 0
	v_pk_add_f32 v[20:21], v[86:87], v[20:21] op_sel:[1,0] op_sel_hi:[0,1]
	v_pk_add_f32 v[20:21], v[86:87], v[20:21]
	s_nop 0
	v_mov_b32_e32 v21, v89
	v_mov_b32_dpp v18, v20 quad_perm:[1,0,3,2] row_mask:0xf bank_mask:0xf bound_ctrl:1
	v_pk_add_f32 v[18:19], v[20:21], v[18:19]
	s_nop 1
	v_mov_b32_dpp v21, v19 quad_perm:[2,3,0,1] row_mask:0xf bank_mask:0xf bound_ctrl:1
	v_mov_b32_dpp v20, v18 quad_perm:[2,3,0,1] row_mask:0xf bank_mask:0xf bound_ctrl:1
	v_pk_add_f32 v[18:19], v[18:19], v[20:21]
	s_nop 1
	v_mov_b32_dpp v21, v19 row_ror:4 row_mask:0xf bank_mask:0xf bound_ctrl:1
	v_mov_b32_dpp v20, v18 row_ror:4 row_mask:0xf bank_mask:0xf bound_ctrl:1
	v_pk_add_f32 v[18:19], v[18:19], v[20:21]
	s_nop 1
	v_mov_b32_dpp v21, v19 row_ror:8 row_mask:0xf bank_mask:0xf bound_ctrl:1
	v_mov_b32_dpp v20, v18 row_ror:8 row_mask:0xf bank_mask:0xf bound_ctrl:1
	v_pk_add_f32 v[18:19], v[18:19], v[20:21]
	ds_bpermute_b32 v21, v37, v19
	ds_bpermute_b32 v20, v37, v18
	s_waitcnt lgkmcnt(0)
	v_pk_add_f32 v[18:19], v[18:19], v[20:21]
	ds_bpermute_b32 v21, v118, v19
	ds_bpermute_b32 v20, v118, v18
	s_waitcnt lgkmcnt(0)
	v_pk_add_f32 v[18:19], v[18:19], v[20:21]
	s_nop 0
	v_pk_fma_f32 v[18:19], v[18:19], s[2:3], v[138:139] op_sel_hi:[1,0,1]
	s_movk_i32 s2, 0xfff
	v_mul_f32_e32 v0, 0x4b800000, v19
	v_cmp_gt_f32_e64 s[8:9], s33, v19
	v_cmp_gt_f32_e32 vcc, s33, v18
	s_nop 0
	v_cndmask_b32_e64 v0, v19, v0, s[8:9]
	v_rsq_f32_e32 v0, v0
	s_nop 0
	v_mul_f32_e32 v19, 0x45800000, v0
	v_cndmask_b32_e64 v84, v0, v19, s[8:9]
	v_mul_f32_e32 v0, 0x4b800000, v18
	v_cndmask_b32_e32 v0, v18, v0, vcc
	v_rsq_f32_e32 v0, v0
	s_nop 0
	v_mul_f32_e32 v18, 0x45800000, v0
	v_cndmask_b32_e32 v86, v0, v18, vcc
	v_pk_mul_f32 v[18:19], v[114:115], v[86:87] op_sel_hi:[1,0]
	v_pk_mul_f32 v[20:21], v[116:117], v[86:87] op_sel_hi:[1,0]
	v_mov_b64_e32 v[114:115], v[176:177]
	v_mov_b64_e32 v[116:117], v[178:179]
	v_mov_b64_e32 v[120:121], v[192:193]
	v_mov_b64_e32 v[122:123], v[194:195]
	v_and_b32_e32 v0, 0xfff, v88
	v_cmp_ne_u32_e64 s[10:11], s2, v0
	v_cmp_eq_u32_e64 s[8:9], 0, v0
	v_cndmask_b32_e64 v0, 0, 1, s[24:25]
	s_and_b64 vcc, exec, s[22:23]
	v_cmp_ne_u32_e64 s[12:13], 1, v0
	v_pk_fma_f32 v[114:115], v[114:115], v[20:21], v[120:121]
	v_pk_fma_f32 v[116:117], v[116:117], v[18:19], v[122:123]
	v_lshlrev_b32_e32 v18, 16, v106
	v_and_b32_e32 v19, 0xffff0000, v106
	v_lshlrev_b32_e32 v20, 16, v107
	v_and_b32_e32 v21, 0xffff0000, v107
	v_pk_mul_f32 v[20:21], v[112:113], v[20:21]
	v_pk_mul_f32 v[18:19], v[110:111], v[18:19]
	v_pk_mul_f32 v[110:111], v[20:21], v[84:85] op_sel_hi:[1,0]
	v_pk_mul_f32 v[106:107], v[18:19], v[84:85] op_sel_hi:[1,0]
	v_mov_b64_e32 v[18:19], v[214:215]
	v_mov_b64_e32 v[20:21], v[216:217]
	v_pk_fma_f32 v[112:113], v[20:21], v[110:111], v[116:117]
	v_pk_fma_f32 v[110:111], v[18:19], v[106:107], v[114:115]
	v_lshl_add_u64 v[18:19], v[54:55], 0, s[28:29]
	v_cvt_pk_bf16_f32 v106, v110, v111
	v_cvt_pk_bf16_f32 v107, v112, v113
	global_store_dwordx4 v[18:19], v[110:113], off nt
	s_cbranch_vccz .LBB0_32
	s_and_b64 vcc, exec, s[12:13]
	s_cbranch_vccnz .LBB0_31
	v_lshl_add_u64 v[20:21], v[52:53], 0, v[46:47]
	global_store_dwordx2 v[20:21], v[106:107], off

.LBB0_37:
	v_mov_b32_e32 v105, v85
	v_mov_b32_e32 v87, v86
	v_mov_b32_e32 v106, v86
	v_mov_b32_e32 v107, v86
	v_mov_b32_e32 v103, v109
	v_pk_mul_f32 v[110:111], v[102:103], v[106:107]
	v_pk_mul_f32 v[112:113], v[104:105], v[86:87]
	v_mov_b64_e32 v[102:103], v[180:181]
	v_mov_b64_e32 v[104:105], v[182:183]
	v_mov_b64_e32 v[106:107], v[196:197]
	v_mov_b64_e32 v[108:109], v[198:199]
	v_mov_b32_e32 v85, v84
	v_cndmask_b32_e64 v0, 0, 1, s[22:23]
	s_mov_b64 s[30:31], -1
	v_cmp_ne_u32_e64 s[14:15], 1, v0
	s_andn2_b64 vcc, exec, s[22:23]
	v_pk_fma_f32 v[102:103], v[112:113], v[102:103], v[106:107]
	v_lshlrev_b32_e32 v106, 16, v82
	v_and_b32_e32 v107, 0xffff0000, v82
	v_lshlrev_b32_e32 v82, 16, v83
	v_and_b32_e32 v83, 0xffff0000, v83
	v_pk_mul_f32 v[98:99], v[98:99], v[106:107]
	v_pk_mul_f32 v[82:83], v[100:101], v[82:83]
	v_pk_mul_f32 v[106:107], v[98:99], v[84:85]
	v_mov_b32_e32 v98, v84
	v_mov_b32_e32 v99, v84
	v_pk_mul_f32 v[82:83], v[82:83], v[98:99]
	v_mov_b64_e32 v[98:99], v[218:219]
	v_mov_b64_e32 v[100:101], v[220:221]
	v_pk_fma_f32 v[104:105], v[110:111], v[104:105], v[108:109]
	v_pk_fma_f32 v[98:99], v[106:107], v[98:99], v[102:103]
	v_pk_fma_f32 v[100:101], v[82:83], v[100:101], v[104:105]
	v_cvt_pk_bf16_f32 v82, v98, v99
	v_cvt_pk_bf16_f32 v83, v100, v101
	global_store_dwordx4 v[18:19], v[98:101], off offset:1024 nt
	s_cbranch_vccnz .LBB0_41
	s_and_b64 vcc, exec, s[12:13]
	s_cbranch_vccnz .LBB0_40
	v_lshl_add_u64 v[98:99], v[52:53], 0, v[46:47]
	global_store_dwordx2 v[98:99], v[82:83], off offset:512

.LBB0_46:
	v_mov_b32_e32 v97, v33
	v_mov_b32_e32 v82, v86
	v_mov_b32_e32 v83, v86
	v_mov_b32_e32 v95, v31
	v_pk_mul_f32 v[82:83], v[94:95], v[82:83]
	v_pk_mul_f32 v[102:103], v[96:97], v[86:87]
	v_mov_b64_e32 v[94:95], v[184:185]
	v_mov_b64_e32 v[96:97], v[186:187]
	v_mov_b64_e32 v[98:99], v[206:207]
	v_mov_b64_e32 v[100:101], v[208:209]
	s_mov_b64 s[30:31], -1
	s_and_b64 vcc, exec, s[14:15]
	v_pk_fma_f32 v[96:97], v[82:83], v[96:97], v[100:101]
	v_lshlrev_b32_e32 v82, 16, v80
	v_and_b32_e32 v83, 0xffff0000, v80
	v_lshlrev_b32_e32 v80, 16, v81
	v_and_b32_e32 v81, 0xffff0000, v81
	v_pk_mul_f32 v[82:83], v[90:91], v[82:83]
	v_pk_mul_f32 v[80:81], v[92:93], v[80:81]
	v_pk_mul_f32 v[90:91], v[82:83], v[84:85]
	v_mov_b32_e32 v82, v84
	v_mov_b32_e32 v83, v84
	v_pk_mul_f32 v[92:93], v[80:81], v[82:83]
	v_mov_b64_e32 v[80:81], v[222:223]
	v_mov_b64_e32 v[82:83], v[224:225]
	v_pk_fma_f32 v[94:95], v[102:103], v[94:95], v[98:99]
	v_pk_fma_f32 v[82:83], v[92:93], v[82:83], v[96:97]
	v_pk_fma_f32 v[80:81], v[90:91], v[80:81], v[94:95]
	global_store_dwordx4 v[18:19], v[80:83], off offset:2048 nt
	s_nop 1
	v_cvt_pk_bf16_f32 v80, v80, v81
	v_cvt_pk_bf16_f32 v81, v82, v83
	s_cbranch_vccnz .LBB0_50
	s_and_b64 vcc, exec, s[12:13]
	s_cbranch_vccnz .LBB0_49
	v_lshl_add_u64 v[82:83], v[52:53], 0, v[46:47]
	global_store_dwordx2 v[82:83], v[80:81], off offset:1024

.LBB0_55:
	v_mov_b64_e32 v[80:81], v[188:189]
	v_mov_b64_e32 v[82:83], v[190:191]
	v_mov_b64_e32 v[90:91], v[210:211]
	v_mov_b64_e32 v[92:93], v[212:213]
	v_mov_b64_e32 v[94:95], v[226:227]
	v_mov_b64_e32 v[96:97], v[228:229]
	v_mov_b32_e32 v23, v30
	v_lshlrev_b32_e32 v30, 16, v34
	v_and_b32_e32 v31, 0xffff0000, v34
	v_mov_b32_e32 v25, v32
	v_mov_b32_e32 v32, v86
	v_mov_b32_e32 v33, v86
	v_lshlrev_b32_e32 v34, 16, v35
	v_and_b32_e32 v35, 0xffff0000, v35
	v_pk_mul_f32 v[26:27], v[26:27], v[30:31]
	v_pk_mul_f32 v[22:23], v[22:23], v[32:33]
	v_pk_mul_f32 v[24:25], v[24:25], v[86:87]
	v_pk_mul_f32 v[28:29], v[28:29], v[34:35]
	v_pk_mul_f32 v[26:27], v[26:27], v[84:85]
	v_mov_b32_e32 v85, v84
	v_pk_mul_f32 v[28:29], v[28:29], v[84:85]
	s_and_b64 vcc, exec, s[14:15]
	s_mov_b64 s[14:15], -1
	s_waitcnt vmcnt(1)
	v_pk_fma_f32 v[22:23], v[22:23], v[82:83], v[92:93]
	v_pk_fma_f32 v[30:31], v[24:25], v[80:81], v[90:91]
	s_waitcnt vmcnt(0)
	v_pk_fma_f32 v[24:25], v[28:29], v[96:97], v[22:23]
	v_pk_fma_f32 v[22:23], v[26:27], v[94:95], v[30:31]
	global_store_dwordx4 v[18:19], v[22:25], off offset:3072 nt
	v_cvt_pk_bf16_f32 v18, v22, v23
	v_cvt_pk_bf16_f32 v19, v24, v25
	s_cbranch_vccnz .LBB0_59
	s_and_b64 vcc, exec, s[12:13]
	s_cbranch_vccnz .LBB0_58
	v_lshl_add_u64 v[22:23], v[52:53], 0, v[46:47]
	global_store_dwordx2 v[22:23], v[18:19], off offset:1536
